# ssd3 prompt B|C conv+SiLU loop body: 8 token chains interleaved, LDS reads batched
# baseline (speedup 1.0000x reference)
.LBB0_335:
	s_andn2_saveexec_b64 s[0:1], s[0:1]
	s_cbranch_execz .LBB0_332
	v_add_u32_e32 v74, s3, v72
	v_add_u32_e32 v74, 0x11800, v74
	ds_read_u16 v150, v74
	ds_read_u16 v151, v74 offset:512
	ds_read_u16 v152, v74 offset:1024
	ds_read_u16 v153, v74 offset:1536
	ds_read_u16 v154, v74 offset:2048
	ds_read_u16 v155, v74 offset:2560
	ds_read_u16 v156, v74 offset:3072
	ds_read_u16 v157, v74 offset:3584
	ds_read_u16 v158, v74 offset:4096
	ds_read_u16 v159, v74 offset:4608
	ds_read_u16 v160, v74 offset:5120
	s_waitcnt lgkmcnt(0)
	v_lshlrev_b32_e32 v161, 16, v150
	v_lshlrev_b32_e32 v162, 16, v151
	v_lshlrev_b32_e32 v163, 16, v152
	v_lshlrev_b32_e32 v164, 16, v153
	v_lshlrev_b32_e32 v165, 16, v154
	v_lshlrev_b32_e32 v166, 16, v155
	v_lshlrev_b32_e32 v167, 16, v156
	v_lshlrev_b32_e32 v168, 16, v157
	v_lshlrev_b32_e32 v169, 16, v158
	v_lshlrev_b32_e32 v170, 16, v159
	v_lshlrev_b32_e32 v171, 16, v160
	v_fma_f32 v172, v116, v161, v111
	v_fma_f32 v173, v116, v162, v111
	v_fma_f32 v174, v116, v163, v111
	v_fma_f32 v175, v116, v164, v111
	v_fma_f32 v176, v116, v165, v111
	v_fma_f32 v177, v116, v166, v111
	v_fma_f32 v178, v116, v167, v111
	v_fma_f32 v179, v116, v168, v111
	v_fmac_f32_e32 v172, v117, v162
	v_fmac_f32_e32 v173, v117, v163
	v_fmac_f32_e32 v174, v117, v164
	v_fmac_f32_e32 v175, v117, v165
	v_fmac_f32_e32 v176, v117, v166
	v_fmac_f32_e32 v177, v117, v167
	v_fmac_f32_e32 v178, v117, v168
	v_fmac_f32_e32 v179, v117, v169
	v_fmac_f32_e32 v172, v118, v163
	v_fmac_f32_e32 v173, v118, v164
	v_fmac_f32_e32 v174, v118, v165
	v_fmac_f32_e32 v175, v118, v166
	v_fmac_f32_e32 v176, v118, v167
	v_fmac_f32_e32 v177, v118, v168
	v_fmac_f32_e32 v178, v118, v169
	v_fmac_f32_e32 v179, v118, v170
	v_fmac_f32_e32 v172, v119, v164
	v_fmac_f32_e32 v173, v119, v165
	v_fmac_f32_e32 v174, v119, v166
	v_fmac_f32_e32 v175, v119, v167
	v_fmac_f32_e32 v176, v119, v168
	v_fmac_f32_e32 v177, v119, v169
	v_fmac_f32_e32 v178, v119, v170
	v_fmac_f32_e32 v179, v119, v171
	v_mul_f32_e32 v180, 0xbfb8aa3b, v172
	v_mul_f32_e32 v181, 0xbfb8aa3b, v173
	v_mul_f32_e32 v182, 0xbfb8aa3b, v174
	v_mul_f32_e32 v183, 0xbfb8aa3b, v175
	v_mul_f32_e32 v184, 0xbfb8aa3b, v176
	v_mul_f32_e32 v185, 0xbfb8aa3b, v177
	v_mul_f32_e32 v186, 0xbfb8aa3b, v178
	v_mul_f32_e32 v187, 0xbfb8aa3b, v179
	v_exp_f32_e32 v180, v180
	v_exp_f32_e32 v181, v181
	v_exp_f32_e32 v182, v182
	v_exp_f32_e32 v183, v183
	v_exp_f32_e32 v184, v184
	v_exp_f32_e32 v185, v185
	v_exp_f32_e32 v186, v186
	v_exp_f32_e32 v187, v187
	v_add_f32_e32 v180, 1.0, v180
	v_add_f32_e32 v181, 1.0, v181
	v_add_f32_e32 v182, 1.0, v182
	v_add_f32_e32 v183, 1.0, v183
	v_add_f32_e32 v184, 1.0, v184
	v_add_f32_e32 v185, 1.0, v185
	v_add_f32_e32 v186, 1.0, v186
	v_add_f32_e32 v187, 1.0, v187
	v_rcp_f32_e32 v180, v180
	v_rcp_f32_e32 v181, v181
	v_rcp_f32_e32 v182, v182
	v_rcp_f32_e32 v183, v183
	v_rcp_f32_e32 v184, v184
	v_rcp_f32_e32 v185, v185
	v_rcp_f32_e32 v186, v186
	v_rcp_f32_e32 v187, v187
	v_mul_f32_e32 v172, v172, v180
	v_mul_f32_e32 v173, v173, v181
	v_mul_f32_e32 v174, v174, v182
	v_mul_f32_e32 v175, v175, v183
	v_mul_f32_e32 v176, v176, v184
	v_mul_f32_e32 v177, v177, v185
	v_mul_f32_e32 v178, v178, v186
	v_mul_f32_e32 v179, v179, v187
	v_cvt_pk_bf16_f32 v172, v172, v191
	v_cvt_pk_bf16_f32 v173, v173, v191
	v_cvt_pk_bf16_f32 v174, v174, v191
	v_cvt_pk_bf16_f32 v175, v175, v191
	v_cvt_pk_bf16_f32 v176, v176, v191
	v_cvt_pk_bf16_f32 v177, v177, v191
	v_cvt_pk_bf16_f32 v178, v178, v191
	v_cvt_pk_bf16_f32 v179, v179, v191
	ds_write_b16 v71, v172
	ds_write_b16 v71, v173 offset:272
	ds_write_b16 v71, v174 offset:544
	ds_write_b16 v71, v175 offset:816
	ds_write_b16 v71, v176 offset:1088
	ds_write_b16 v71, v177 offset:1360
	ds_write_b16 v71, v178 offset:1632
	ds_write_b16 v71, v179 offset:1904
	s_branch .LBB0_332
